# mem-attention QK LDS reads pipelined (4-temp ring, counted lgkmcnt) + static s_setprio removed from the two attention loops; bit-identical output
# speedup vs baseline: 1.0028x; 1.0028x over previous
; __device__ __forceinline__ int v_rd_base(int lane) { return ((lane & 3) << 3) | (((lane >> 2) & 3) << 6) | (((lane >> 4) & 1) << 5) | (((lane >> 5) & 1) << 8); }
; template <int LD>
; __device__ __forceinline__ void attn256_body(const bf16_t* __restrict__ Qb, const bf16_t* __restrict__ Kh, const unsigned char* __restrict__ Vimg, int seq, char* lds, LAS unsigned char* ldsl,
;                                              f32x16 (&o)[8], float (&rli)[16]) {
;   int tid = TIDX(); asm volatile("" : "+v"(tid));
;   const int wid = __builtin_amdgcn_readfirstlane(tid >> 6), lane = tid & 63, r32 = lane & 31, hi = lane >> 5;
;   float* wsf = (float*)(lds + LDS_XCH) + wid * 64; float* li_l = wsf; float* al_l = wsf + 32;
;   float m_reg = -1e30f, l_reg = 0.f; bf16x8 qr[8];
; #pragma unroll
;   for (int d = 0; d < 8; ++d) o[d] = f32x16{};
;   const bf16_t* Qw = Qb + (size_t)(wid * 32 + r32) * LD + hi * 8;
; #pragma unroll
;   for (int d0 = 0; d0 < 8; ++d0) qr[d0] = *(const bf16x8*)(Qw + d0 * 16);
;   unsigned voffK[2], voffV[2];
; #pragma unroll
;   for (int i = 0; i < 2; ++i) { const int b = (i * 512 + tid) * 16;
;     { const int row = b >> 8, cB = (b & 255) ^ ((row & 7) << 4); voffK[i] = (unsigned)(row * LD) * 2u + (unsigned)cB; }
;     { const int st = b >> 9, w = b & 511, kk = (st >> 2) * 8 + (w >> 6), c = (st & 3) * 32 + ((w & 63) >> 1);
;       (void)kk; (void)c; voffV[i] = (unsigned)tid * 16u; } }
;   const unsigned ldsw = (unsigned)wid * 1024u;
;     ...
;   const int NT = seq / 64;
;   const int vb0 = (int)(uintptr_t)lds + 16384 + v_rd_base(lane);
;   const int kbase = (int)(uintptr_t)lds + r32 * 256;
;   constexpr float C = ATT_SCALE * LOG2E;
;   __syncthreads();
;   A2_DMA(0, 0);
;   asm volatile("s_waitcnt vmcnt(0)" ::: "memory"); __syncthreads();
;   if (wid >= 4) __builtin_amdgcn_s_setprio(1);
.LBB0_659:
	s_getreg_b32 s0, hwreg(HW_REG_HW_ID, 0, 6)
	s_lshl_b32 s0, s0, 2
	s_and_b32 s0, s0, 0xfc
	s_add_i32 s0, s0, 0x24c40
	v_mov_b32_e32 v0, s0
	ds_read_b32 v0, v0
	s_lshl_b32 s0, s65, 5
	s_and_b32 s40, s0, 0xffffff00
	s_ashr_i32 s41, s40, 31
	s_and_b32 s4, s65, 7
	s_waitcnt lgkmcnt(0)
	v_readfirstlane_b32 s0, v0
	v_mbcnt_lo_u32_b32 v2, -1, 0
	v_mbcnt_hi_u32_b32 v2, -1, v2
	v_mov_b32_e32 v221, v1
	s_mov_b64 s[8:9], 0x100
	v_lshl_add_u32 v218, s0, 6, v2
	s_lshl_b64 s[0:1], s[40:41], 14
	s_add_u32 s0, s46, s0
	s_addc_u32 s1, s47, s1
	s_lshl_b32 s5, s4, 9
	s_add_u32 s34, s0, s5
	s_addc_u32 s35, s1, 0
	s_add_u32 s24, s95, s5
	v_readlane_b32 s0, v255, 10
	s_addc_u32 s25, s0, 0
	s_lshl_b32 s0, s4, 23
	s_add_u32 s12, s16, s0
	s_getreg_b32 s0, hwreg(HW_REG_HW_ID, 0, 6)
	s_addc_u32 s13, s17, 0
	s_lshl_b32 s0, s0, 2
	s_and_b32 s0, s0, 0xfc
	s_add_i32 s0, s0, 0x24c40
	v_mov_b32_e32 v0, s0
	ds_read_b32 v0, v0
	v_mbcnt_lo_u32_b32 v2, -1, 0
	v_mbcnt_hi_u32_b32 v2, -1, v2
	v_mov_b32_e32 v11, v1
	s_waitcnt lgkmcnt(0)
	v_readfirstlane_b32 s0, v0
	s_nop 1
	v_lshl_add_u32 v3, s0, 6, v2
	s_nop 0
	v_readfirstlane_b32 s5, v3
	s_ashr_i32 s6, s5, 6
	v_and_b32_e32 v4, 31, v3
	v_lshl_or_b32 v6, s6, 5, v4
	v_ashrrev_i32_e32 v7, 31, v6
	v_bfe_u32 v2, v3, 5, 1
	v_lshlrev_b64 v[6:7], 14, v[6:7]
	v_lshl_add_u64 v[6:7], s[34:35], 0, v[6:7]
	v_lshlrev_b32_e32 v220, 4, v2
	v_bfe_i32 v0, v3, 4, 24
	v_lshl_add_u64 v[6:7], v[6:7], 0, v[220:221]
	v_lshlrev_b32_e32 v14, 4, v3
	v_lshlrev_b32_e32 v8, 4, v0
	global_load_dwordx4 v[176:179], v[6:7], off offset:256
	global_load_dwordx4 v[180:183], v[6:7], off offset:288
	global_load_dwordx4 v[184:187], v[6:7], off offset:320
	global_load_dwordx4 v[188:191], v[6:7], off offset:352
	global_load_dwordx4 v[192:195], v[6:7], off offset:384
	global_load_dwordx4 v[196:199], v[6:7], off offset:416
	global_load_dwordx4 v[200:203], v[6:7], off offset:448
	global_load_dwordx4 v[204:207], v[6:7], off offset:480
	v_and_b32_e32 v7, 0xf0, v14
	v_and_b32_e32 v6, 0x70, v8
	v_lshlrev_b32_e32 v5, 14, v0
	v_bitop3_b32 v0, v6, v5, v7 bitop3:0xde
	v_add_u32_e32 v6, 0x2000, v14
	v_ashrrev_i32_e32 v6, 8, v6
	v_lshlrev_b32_e32 v9, 4, v6
	v_and_b32_e32 v10, 0x70, v9
	v_lshlrev_b32_e32 v6, 14, v6
	s_lshl_b32 s0, s6, 10
	v_bitop3_b32 v10, v10, v6, v7 bitop3:0xde
	s_add_i32 s0, s0, 0
	v_lshl_add_u64 v[12:13], s[24:25], 0, v[0:1]
	v_lshl_add_u64 v[12:13], v[12:13], 0, s[8:9]
	s_mov_b32 m0, s0
	v_lshl_add_u64 v[10:11], s[24:25], 0, v[10:11]
	s_barrier
	global_load_lds_dwordx4 v[12:13], off
	v_lshl_add_u64 v[10:11], v[10:11], 0, s[8:9]
	s_add_i32 m0, s0, 0x2000
	v_mov_b32_e32 v0, v14
	s_add_i32 s1, s0, 0x4000
	global_load_lds_dwordx4 v[10:11], off
	v_lshl_add_u64 v[10:11], s[12:13], 0, v[0:1]
	s_mov_b32 m0, s1
	s_add_i32 s28, s0, 0x6000
	global_load_lds_dwordx4 v14, s[12:13]
	v_lshl_add_u64 v[12:13], v[10:11], 0, s[54:55]
	s_mov_b32 m0, s28
	s_mov_b64 s[8:9], 0x4000
	s_add_i32 s29, s0, 0x8000
	global_load_lds_dwordx4 v[12:13], off
	v_lshl_add_u64 v[12:13], v[10:11], 0, s[8:9]
	s_mov_b32 m0, s29
	s_mov_b64 s[8:9], 0x6000
	s_add_i32 s52, s0, 0xa000
	global_load_lds_dwordx4 v[12:13], off
	v_lshl_add_u64 v[10:11], v[10:11], 0, s[8:9]
	s_mov_b32 m0, s52
	s_cmp_lt_i32 s6, 4
	global_load_lds_dwordx4 v[10:11], off
	s_waitcnt vmcnt(0)
	s_waitcnt vmcnt(0) lgkmcnt(0)
	s_barrier
	s_cbranch_scc1 .LBB0_661
; __device__ __forceinline__ int v_rd_base(int lane) { return ((lane & 3) << 3) | (((lane >> 2) & 3) << 6) | (((lane >> 4) & 1) << 5) | (((lane >> 5) & 1) << 8); }
; template <int LD>
; __device__ __forceinline__ void attn256_body(const bf16_t* __restrict__ Qb, const bf16_t* __restrict__ Kh, const unsigned char* __restrict__ Vimg, int seq, char* lds, LAS unsigned char* ldsl,
;                                              f32x16 (&o)[8], float (&rli)[16]) {
;     ...
;   const int wid = __builtin_amdgcn_readfirstlane(tid >> 6), lane = tid & 63, r32 = lane & 31, hi = lane >> 5;
;   float* wsf = (float*)(lds + LDS_XCH) + wid * 64; float* li_l = wsf; float* al_l = wsf + 32;
;   float m_reg = -1e30f, l_reg = 0.f; bf16x8 qr[8];
; #pragma unroll
;   for (int d = 0; d < 8; ++d) o[d] = f32x16{};
;   const bf16_t* Qw = Qb + (size_t)(wid * 32 + r32) * LD + hi * 8;
; #pragma unroll
;   for (int d0 = 0; d0 < 8; ++d0) qr[d0] = *(const bf16x8*)(Qw + d0 * 16);
;   unsigned voffK[2], voffV[2];
; #pragma unroll
;   for (int i = 0; i < 2; ++i) { const int b = (i * 512 + tid) * 16;
;     { const int row = b >> 8, cB = (b & 255) ^ ((row & 7) << 4); voffK[i] = (unsigned)(row * LD) * 2u + (unsigned)cB; }
;     { const int st = b >> 9, w = b & 511, kk = (st >> 2) * 8 + (w >> 6), c = (st & 3) * 32 + ((w & 63) >> 1);
;       (void)kk; (void)c; voffV[i] = (unsigned)tid * 16u; } }
;   const unsigned ldsw = (unsigned)wid * 1024u;
;     ...
;   const int NT = seq / 64;
;   const int vb0 = (int)(uintptr_t)lds + 16384 + v_rd_base(lane);
;   const int kbase = (int)(uintptr_t)lds + r32 * 256;
;   constexpr float C = ATT_SCALE * LOG2E;
;   __syncthreads();
;   A2_DMA(0, 0);
;   asm volatile("s_waitcnt vmcnt(0)" ::: "memory"); __syncthreads();
;   if (wid >= 4) __builtin_amdgcn_s_setprio(1);
;   for (int j = 0; j < NT; ++j) {
;     const int cur = j & 1;
;     if (j + 1 < NT) { if (cur) A2_DMA(0, (j + 1) * 64); else A2_DMA(1, (j + 1) * 64); }
;     f32x16 p0 = f32x16{}, p1 = f32x16{}; float pmax;
;     { int ka[4];
; #pragma unroll
;       for (int q = 0; q < 4; ++q) ka[q] = kbase + cur * A2_STAGE + (((2 * q + hi) ^ (r32 & 7)) << 4);
.LBB0_661:
	s_lshl_b32 s85, s4, 8
	s_and_b32 s4, s64, 7
	s_lshl_b32 s10, s4, 23
	s_lshl_b32 s36, s4, 9
	s_and_b32 s4, s5, 0x3fffffc0
	s_lshl_b32 s4, s4, 2
	s_add_i32 s53, s4, 0
	v_and_b32_e32 v10, 63, v3
	s_add_i32 s53, s53, 0x24000
	v_and_b32_e32 v13, 7, v3
	v_bitop3_b32 v3, v2, v3, 7 bitop3:0x78
	v_bitop3_b32 v8, v8, v7, s91 bitop3:0x6c
	v_bitop3_b32 v7, v9, v7, s91 bitop3:0x6c
	v_lshlrev_b32_e32 v11, 1, v10
	s_cmp_lg_u32 0, -1
	v_lshlrev_b32_e32 v233, 4, v3
	v_bitop3_b32 v3, v2, v13, 2 bitop3:0x36
	v_lshlrev_b32_e32 v9, 4, v10
	v_lshlrev_b32_e32 v12, 3, v10
	v_and_b32_e32 v11, 32, v11
	s_mov_b32 s45, 0
	s_cselect_b32 s4, 0, 0
	v_lshlrev_b32_e32 v234, 4, v3
	v_bitop3_b32 v3, v2, v13, 4 bitop3:0x36
	v_bitop3_b32 v2, v2, v13, 6 bitop3:0x36
	s_movk_i32 s5, 0x118
	v_lshl_add_u64 v[222:223], s[10:11], 0, v[0:1]
	s_or_b32 s44, s36, 0xa901100
	v_add_u32_e32 v0, v7, v6
	v_and_b32_e32 v9, 0xc0, v9
	v_lshl_add_u32 v221, v4, 8, s4
	v_lshlrev_b32_e32 v236, 4, v2
	v_and_or_b32 v2, v12, s5, v11
	s_addk_i32 s4, 0x4000
	v_lshl_add_u64 v[224:225], s[44:45], 0, v[0:1]
	v_add_u32_e32 v0, v8, v5
	v_mov_b32_e32 v14, v1
	v_mov_b32_e32 v15, v1
	v_cmp_gt_u32_e64 s[38:39], 32, v10
	v_lshl_add_u32 v219, v4, 2, s53
	v_lshlrev_b32_e32 v235, 4, v3
	v_add3_u32 v237, v9, s4, v2
	v_lshl_add_u64 v[226:227], s[44:45], 0, v[0:1]
	v_mov_b32_e32 v0, v1
	v_mov_b32_e32 v2, v1
	v_mov_b32_e32 v3, v1
	v_mov_b32_e32 v4, v1
	v_mov_b32_e32 v5, v1
	v_mov_b32_e32 v6, v1
	v_mov_b32_e32 v7, v1
	v_mov_b32_e32 v8, v1
	v_mov_b32_e32 v9, v1
	v_mov_b32_e32 v10, v1
	v_mov_b32_e32 v11, v1
	v_mov_b32_e32 v12, v1
	v_mov_b32_e32 v13, v1
	v_mov_b64_e32 v[30:31], v[14:15]
	v_mov_b64_e32 v[46:47], v[14:15]
	v_mov_b64_e32 v[62:63], v[14:15]
	v_mov_b64_e32 v[78:79], v[14:15]
	v_mov_b64_e32 v[94:95], v[14:15]
	v_mov_b64_e32 v[110:111], v[14:15]
	v_mov_b64_e32 v[126:127], v[14:15]
	v_mov_b64_e32 v[142:143], v[14:15]
	s_mov_b32 s37, s11
	s_add_i32 s56, s0, 0xc000
	s_add_i32 s57, s0, 0x10000
	s_add_i32 s60, s0, 0x12000
	s_add_i32 s61, s0, 0x14000
	s_add_i32 s62, s0, 0x16000
	v_mov_b32_e32 v239, 0
	v_mov_b32_e32 v238, 0xf149f2ca
	v_mov_b64_e32 v[28:29], v[12:13]
	v_mov_b64_e32 v[26:27], v[10:11]
	v_mov_b64_e32 v[24:25], v[8:9]
	v_mov_b64_e32 v[22:23], v[6:7]
	v_mov_b64_e32 v[20:21], v[4:5]
	v_mov_b64_e32 v[18:19], v[2:3]
	v_mov_b64_e32 v[16:17], v[0:1]
	v_mov_b64_e32 v[44:45], v[12:13]
	v_mov_b64_e32 v[42:43], v[10:11]
	v_mov_b64_e32 v[40:41], v[8:9]
	v_mov_b64_e32 v[38:39], v[6:7]
	v_mov_b64_e32 v[36:37], v[4:5]
	v_mov_b64_e32 v[34:35], v[2:3]
	v_mov_b64_e32 v[32:33], v[0:1]
	v_mov_b64_e32 v[60:61], v[12:13]
	v_mov_b64_e32 v[58:59], v[10:11]
	v_mov_b64_e32 v[56:57], v[8:9]
	v_mov_b64_e32 v[54:55], v[6:7]
	v_mov_b64_e32 v[52:53], v[4:5]
	v_mov_b64_e32 v[50:51], v[2:3]
	v_mov_b64_e32 v[48:49], v[0:1]
	v_mov_b64_e32 v[76:77], v[12:13]
	v_mov_b64_e32 v[74:75], v[10:11]
	v_mov_b64_e32 v[72:73], v[8:9]
	v_mov_b64_e32 v[70:71], v[6:7]
	v_mov_b64_e32 v[68:69], v[4:5]
	v_mov_b64_e32 v[66:67], v[2:3]
	v_mov_b64_e32 v[64:65], v[0:1]
	v_mov_b64_e32 v[92:93], v[12:13]
	v_mov_b64_e32 v[90:91], v[10:11]
	v_mov_b64_e32 v[88:89], v[8:9]
	v_mov_b64_e32 v[86:87], v[6:7]
	v_mov_b64_e32 v[84:85], v[4:5]
	v_mov_b64_e32 v[82:83], v[2:3]
	v_mov_b64_e32 v[80:81], v[0:1]
	v_mov_b64_e32 v[108:109], v[12:13]
	v_mov_b64_e32 v[106:107], v[10:11]
	v_mov_b64_e32 v[104:105], v[8:9]
	v_mov_b64_e32 v[102:103], v[6:7]
	v_mov_b64_e32 v[100:101], v[4:5]
	v_mov_b64_e32 v[98:99], v[2:3]
	v_mov_b64_e32 v[96:97], v[0:1]
	v_mov_b64_e32 v[124:125], v[12:13]
	v_mov_b64_e32 v[122:123], v[10:11]
	v_mov_b64_e32 v[120:121], v[8:9]
	v_mov_b64_e32 v[118:119], v[6:7]
	v_mov_b64_e32 v[116:117], v[4:5]
	v_mov_b64_e32 v[114:115], v[2:3]
	v_mov_b64_e32 v[112:113], v[0:1]
	v_mov_b64_e32 v[140:141], v[12:13]
	v_mov_b64_e32 v[138:139], v[10:11]
	v_mov_b64_e32 v[136:137], v[8:9]
	v_mov_b64_e32 v[134:135], v[6:7]
	v_mov_b64_e32 v[132:133], v[4:5]
	v_mov_b64_e32 v[130:131], v[2:3]
	v_mov_b64_e32 v[128:129], v[0:1]
	s_and_b32 s4, s45, 1
	s_cmpk_eq_i32 s45, 0xff
	s_cbranch_scc1 .LBB0_663

; #define LAS __attribute__((address_space(3)))
; __device__ __forceinline__ unsigned cvtpk(float lo, float hi) { unsigned r; asm volatile("v_cvt_pk_bf16_f32 %0, %1, %2" : "=v"(r) : "v"(lo), "v"(hi)); return r; }
; #define SBAR() __builtin_amdgcn_sched_barrier(0)
; __device__ __forceinline__ int crow(int r, int hi) { return (r & 3) + 8 * (r >> 2) + 4 * hi; }
; template <int LD>
; __device__ __forceinline__ void attn256_body(const bf16_t* __restrict__ Qb, const bf16_t* __restrict__ Kh, const unsigned char* __restrict__ Vimg, int seq, char* lds, LAS unsigned char* ldsl,
;                                              f32x16 (&o)[8], float (&rli)[16]) {
;     ...
;   __builtin_amdgcn_s_setprio(0);
;   if (hi == 0) li_l[r32] = l_reg; asm volatile("s_waitcnt lgkmcnt(0)" ::: "memory");
; #pragma unroll
;   for (int r = 0; r < 16; ++r) rli[r] = __builtin_amdgcn_rcpf(li_l[crow(r, hi)]);
;     ...
; }
; __device__ __forceinline__ void diff_item256(const Params& P, int h, int qb, float lam, char* lds, LAS unsigned char* ldsl) {
;   int tid = TIDX(); asm volatile("" : "+v"(tid));
;   const int wid = tid >> 6, lane = tid & 63, r32 = lane & 31, hi = lane >> 5;
;   bf16_t* proj = (bf16_t*)(P.ws + OFF_PROJ);
;   unsigned* scrw = (unsigned*)(P.ws + OFF_SCR) + (size_t)blockIdx.x * 32768;
;   f32x16 o[8]; float rli[16];
;   attn256_body<8192>(proj + (size_t)(qb * 256) * 8192 + 256 * h + 128, proj + 2048 + 256 * h + 128, P.ws + OFF_STATE + (size_t)h * 256 * 32768, TB, lds, ldsl, o, rli);
;   { unsigned* sp = scrw + tid; asm volatile("" : "+v"(sp));
; #pragma unroll
;     for (int d = 0; d < 8; ++d)
; #pragma unroll
;       for (int r = 0; r < 16; r += 2) { sp[(d * 8 + (r >> 1)) * 512] = cvtpk(o[d][r] * rli[r], o[d][r + 1] * rli[r + 1]); if (r == 14 && (d & 1)) SBAR(); } }
.LBB0_671:
	s_setprio 0
	s_and_saveexec_b64 s[44:45], s[38:39]
	ds_write_b32 v219, v2
	s_or_b64 exec, exec, s[44:45]
	s_waitcnt lgkmcnt(0)
	v_add_u32_e32 v0, s53, v220
	ds_read_b128 v[2:5], v0
	ds_read_b128 v[6:9], v0 offset:32
	v_readlane_b32 s0, v254, 43
	v_ashrrev_i32_e32 v219, 31, v218
	v_readlane_b32 s1, v254, 44
	s_waitcnt lgkmcnt(1)
	v_rcp_f32_e32 v10, v2
	v_rcp_f32_e32 v11, v3
	v_rcp_f32_e32 v12, v4
	v_rcp_f32_e32 v13, v5
	ds_read_b128 v[2:5], v0 offset:64
	v_lshl_add_u64 v[210:211], v[218:219], 2, s[0:1]
	s_waitcnt lgkmcnt(1)
	v_rcp_f32_e32 v14, v6
	v_rcp_f32_e32 v15, v7
	v_rcp_f32_e32 v144, v8
	v_rcp_f32_e32 v145, v9
	ds_read_b128 v[6:9], v0 offset:96
	s_waitcnt lgkmcnt(1)
	v_rcp_f32_e32 v0, v2
	v_rcp_f32_e32 v146, v3
	v_rcp_f32_e32 v147, v4
	v_mov_b64_e32 v[2:3], v[210:211]
	v_mul_f32_e32 v4, v128, v10
	v_rcp_f32_e32 v148, v5
	v_mul_f32_e32 v5, v129, v11
	v_cvt_pk_bf16_f32 v4, v4, v5
	flat_store_dword v[2:3], v4
	v_mul_f32_e32 v4, v130, v12
	v_mul_f32_e32 v5, v131, v13
	v_cvt_pk_bf16_f32 v4, v4, v5
	flat_store_dword v[2:3], v4 offset:2048
	v_mul_f32_e32 v4, v132, v14
	s_movk_i32 s0, 0x1000
	v_mul_f32_e32 v5, v133, v15
	v_cvt_pk_bf16_f32 v128, v4, v5
	v_add_co_u32_e32 v4, vcc, s0, v2
	s_waitcnt lgkmcnt(0)
	v_rcp_f32_e32 v6, v6
	v_addc_co_u32_e32 v5, vcc, 0, v3, vcc
	flat_store_dword v[4:5], v128
	v_mul_f32_e32 v128, v134, v144
	v_mul_f32_e32 v129, v135, v145
	v_cvt_pk_bf16_f32 v128, v128, v129
	flat_store_dword v[4:5], v128 offset:2048
	v_mul_f32_e32 v4, v136, v0
	s_movk_i32 s0, 0x2000
	v_rcp_f32_e32 v7, v7
	v_mul_f32_e32 v5, v137, v146
	v_cvt_pk_bf16_f32 v128, v4, v5
	v_add_co_u32_e32 v4, vcc, s0, v2
	v_rcp_f32_e32 v8, v8
	s_nop 0
	v_addc_co_u32_e32 v5, vcc, 0, v3, vcc
	flat_store_dword v[4:5], v128
	v_mul_f32_e32 v128, v138, v147
	v_rcp_f32_e32 v9, v9
	v_mul_f32_e32 v129, v139, v148
	v_cvt_pk_bf16_f32 v128, v128, v129
	flat_store_dword v[4:5], v128 offset:2048
	v_mul_f32_e32 v4, v140, v6
	v_mul_f32_e32 v5, v141, v7
	v_cvt_pk_bf16_f32 v128, v4, v5
	v_add_co_u32_e32 v4, vcc, s67, v2
	v_mul_f32_e32 v129, v143, v9
	s_nop 0
	v_addc_co_u32_e32 v5, vcc, 0, v3, vcc
	flat_store_dword v[4:5], v128
	v_mul_f32_e32 v128, v142, v8
	v_cvt_pk_bf16_f32 v128, v128, v129
	flat_store_dword v[4:5], v128 offset:2048
	v_mul_f32_e32 v4, v112, v10
	v_mul_f32_e32 v5, v113, v11
	v_cvt_pk_bf16_f32 v112, v4, v5
	v_add_co_u32_e32 v4, vcc, s66, v2
	v_mul_f32_e32 v113, v115, v13
	s_nop 0
	v_addc_co_u32_e32 v5, vcc, 0, v3, vcc
	flat_store_dword v[4:5], v112
	v_mul_f32_e32 v112, v114, v12
	v_cvt_pk_bf16_f32 v112, v112, v113
	flat_store_dword v[4:5], v112 offset:2048
	v_mul_f32_e32 v4, v116, v14
	s_movk_i32 s0, 0x5000
	v_mul_f32_e32 v5, v117, v15
	v_cvt_pk_bf16_f32 v112, v4, v5
	v_add_co_u32_e32 v4, vcc, s0, v2
	v_mul_f32_e32 v113, v119, v145
	s_nop 0
	v_addc_co_u32_e32 v5, vcc, 0, v3, vcc
	flat_store_dword v[4:5], v112
	v_mul_f32_e32 v112, v118, v144
	v_cvt_pk_bf16_f32 v112, v112, v113
	flat_store_dword v[4:5], v112 offset:2048
	v_mul_f32_e32 v4, v120, v0
	s_movk_i32 s0, 0x6000
	v_mul_f32_e32 v5, v121, v146
	v_cvt_pk_bf16_f32 v112, v4, v5
	v_add_co_u32_e32 v4, vcc, s0, v2
	v_mul_f32_e32 v113, v123, v148
	s_nop 0
	v_addc_co_u32_e32 v5, vcc, 0, v3, vcc
	flat_store_dword v[4:5], v112
	v_mul_f32_e32 v112, v122, v147
	v_cvt_pk_bf16_f32 v112, v112, v113
	flat_store_dword v[4:5], v112 offset:2048
	v_mul_f32_e32 v4, v124, v6
	s_movk_i32 s0, 0x7000
	v_mul_f32_e32 v5, v125, v7
	v_cvt_pk_bf16_f32 v112, v4, v5
	v_add_co_u32_e32 v4, vcc, s0, v2
	v_mul_f32_e32 v113, v127, v9
	s_nop 0
	v_addc_co_u32_e32 v5, vcc, 0, v3, vcc
	flat_store_dword v[4:5], v112
	v_mul_f32_e32 v112, v126, v8
	v_cvt_pk_bf16_f32 v112, v112, v113
	flat_store_dword v[4:5], v112 offset:2048
	v_mul_f32_e32 v4, v96, v10
	v_mul_f32_e32 v5, v97, v11
	v_cvt_pk_bf16_f32 v96, v4, v5
	v_add_co_u32_e32 v4, vcc, s88, v2
	v_mul_f32_e32 v97, v99, v13
	s_nop 0
	v_addc_co_u32_e32 v5, vcc, 0, v3, vcc
	flat_store_dword v[4:5], v96
	v_mul_f32_e32 v96, v98, v12
	v_cvt_pk_bf16_f32 v96, v96, v97
	flat_store_dword v[4:5], v96 offset:2048
	v_mul_f32_e32 v4, v100, v14
	s_mov_b32 s0, 0x9000
	v_mul_f32_e32 v5, v101, v15
	v_cvt_pk_bf16_f32 v96, v4, v5
	v_add_co_u32_e32 v4, vcc, s0, v2
	v_mul_f32_e32 v97, v103, v145
	s_nop 0
	v_addc_co_u32_e32 v5, vcc, 0, v3, vcc
	flat_store_dword v[4:5], v96
	v_mul_f32_e32 v96, v102, v144
	v_cvt_pk_bf16_f32 v96, v96, v97
	flat_store_dword v[4:5], v96 offset:2048
	v_mul_f32_e32 v4, v104, v0
	s_mov_b32 s0, 0xa000
	v_mul_f32_e32 v5, v105, v146
	v_cvt_pk_bf16_f32 v96, v4, v5
	v_add_co_u32_e32 v4, vcc, s0, v2
	v_mul_f32_e32 v97, v107, v148
	s_nop 0
	v_addc_co_u32_e32 v5, vcc, 0, v3, vcc
	flat_store_dword v[4:5], v96
	v_mul_f32_e32 v96, v106, v147
	v_cvt_pk_bf16_f32 v96, v96, v97
	flat_store_dword v[4:5], v96 offset:2048
	v_mul_f32_e32 v4, v108, v6
	s_mov_b32 s0, 0xb000
	v_mul_f32_e32 v5, v109, v7
	v_cvt_pk_bf16_f32 v96, v4, v5
	v_add_co_u32_e32 v4, vcc, s0, v2
	v_mul_f32_e32 v97, v111, v9
	s_nop 0
	v_addc_co_u32_e32 v5, vcc, 0, v3, vcc
	flat_store_dword v[4:5], v96
	v_mul_f32_e32 v96, v110, v8
	v_cvt_pk_bf16_f32 v96, v96, v97
	flat_store_dword v[4:5], v96 offset:2048
	v_mul_f32_e32 v4, v80, v10
	s_mov_b32 s0, 0xc000
	v_mul_f32_e32 v5, v81, v11
	v_cvt_pk_bf16_f32 v80, v4, v5
	v_add_co_u32_e32 v4, vcc, s0, v2
	v_mul_f32_e32 v81, v83, v13
	s_nop 0
	v_addc_co_u32_e32 v5, vcc, 0, v3, vcc
	flat_store_dword v[4:5], v80
	v_mul_f32_e32 v80, v82, v12
	v_cvt_pk_bf16_f32 v80, v80, v81
	flat_store_dword v[4:5], v80 offset:2048
	v_mul_f32_e32 v4, v84, v14
	s_mov_b32 s0, 0xd000
	v_mul_f32_e32 v5, v85, v15
	v_cvt_pk_bf16_f32 v80, v4, v5
	v_add_co_u32_e32 v4, vcc, s0, v2
	v_mul_f32_e32 v81, v87, v145
	s_nop 0
; __device__ __forceinline__ unsigned cvtpk(float lo, float hi) { unsigned r; asm volatile("v_cvt_pk_bf16_f32 %0, %1, %2" : "=v"(r) : "v"(lo), "v"(hi)); return r; }
; #define SBAR() __builtin_amdgcn_sched_barrier(0)
; __device__ __forceinline__ void diff_item256(const Params& P, int h, int qb, float lam, char* lds, LAS unsigned char* ldsl) {
;     ...
;   { unsigned* sp = scrw + tid; asm volatile("" : "+v"(sp));
; #pragma unroll
;     for (int d = 0; d < 8; ++d)
; #pragma unroll
;       for (int r = 0; r < 16; r += 2) { sp[(d * 8 + (r >> 1)) * 512] = cvtpk(o[d][r] * rli[r], o[d][r + 1] * rli[r + 1]); if (r == 14 && (d & 1)) SBAR(); } }
;   attn256_body<8192>(proj + (size_t)(qb * 256) * 8192 + 256 * h, proj + 2048 + 256 * h, P.ws + OFF_STATE + (size_t)h * 256 * 32768, TB, lds, ldsl, o, rli);
	v_addc_co_u32_e32 v5, vcc, 0, v3, vcc
	flat_store_dword v[4:5], v80
	v_mul_f32_e32 v80, v86, v144
	v_cvt_pk_bf16_f32 v80, v80, v81
	flat_store_dword v[4:5], v80 offset:2048
	v_mul_f32_e32 v4, v88, v0
	v_mul_f32_e32 v5, v89, v146
	v_cvt_pk_bf16_f32 v80, v4, v5
	v_add_co_u32_e32 v4, vcc, s89, v2
	v_mul_f32_e32 v81, v91, v148
	s_nop 0
	v_addc_co_u32_e32 v5, vcc, 0, v3, vcc
	flat_store_dword v[4:5], v80
	v_mul_f32_e32 v80, v90, v147
	v_cvt_pk_bf16_f32 v80, v80, v81
	flat_store_dword v[4:5], v80 offset:2048
	v_mul_f32_e32 v4, v92, v6
	s_mov_b32 s0, 0xf000
	v_mul_f32_e32 v5, v93, v7
	v_cvt_pk_bf16_f32 v80, v4, v5
	v_add_co_u32_e32 v4, vcc, s0, v2
	v_mul_f32_e32 v81, v95, v9
	s_nop 0
	v_addc_co_u32_e32 v5, vcc, 0, v3, vcc
	flat_store_dword v[4:5], v80
	v_mul_f32_e32 v80, v94, v8
	v_cvt_pk_bf16_f32 v80, v80, v81
	flat_store_dword v[4:5], v80 offset:2048
	v_mul_f32_e32 v4, v64, v10
	v_mul_f32_e32 v5, v65, v11
	v_cvt_pk_bf16_f32 v64, v4, v5
	v_add_co_u32_e32 v4, vcc, s90, v2
	v_mul_f32_e32 v65, v67, v13
	s_nop 0
	v_addc_co_u32_e32 v5, vcc, 0, v3, vcc
	flat_store_dword v[4:5], v64
	v_mul_f32_e32 v64, v66, v12
	v_cvt_pk_bf16_f32 v64, v64, v65
	flat_store_dword v[4:5], v64 offset:2048
	v_mul_f32_e32 v4, v68, v14
	s_mov_b32 s0, 0x11000
	v_mul_f32_e32 v5, v69, v15
	v_cvt_pk_bf16_f32 v64, v4, v5
	v_add_co_u32_e32 v4, vcc, s0, v2
	v_mul_f32_e32 v65, v71, v145
	s_nop 0
	v_addc_co_u32_e32 v5, vcc, 0, v3, vcc
	flat_store_dword v[4:5], v64
	v_mul_f32_e32 v64, v70, v144
	v_cvt_pk_bf16_f32 v64, v64, v65
	flat_store_dword v[4:5], v64 offset:2048
	v_mul_f32_e32 v4, v72, v0
	s_mov_b32 s0, 0x12000
	v_mul_f32_e32 v5, v73, v146
	v_cvt_pk_bf16_f32 v64, v4, v5
	v_add_co_u32_e32 v4, vcc, s0, v2
	v_mul_f32_e32 v65, v75, v148
	s_nop 0
	v_addc_co_u32_e32 v5, vcc, 0, v3, vcc
	flat_store_dword v[4:5], v64
	v_mul_f32_e32 v64, v74, v147
	v_cvt_pk_bf16_f32 v64, v64, v65
	flat_store_dword v[4:5], v64 offset:2048
	v_mul_f32_e32 v4, v76, v6
	s_mov_b32 s0, 0x13000
	v_mul_f32_e32 v5, v77, v7
	v_cvt_pk_bf16_f32 v64, v4, v5
	v_add_co_u32_e32 v4, vcc, s0, v2
	v_mul_f32_e32 v65, v79, v9
	s_nop 0
	v_addc_co_u32_e32 v5, vcc, 0, v3, vcc
	flat_store_dword v[4:5], v64
	v_mul_f32_e32 v64, v78, v8
	v_cvt_pk_bf16_f32 v64, v64, v65
	flat_store_dword v[4:5], v64 offset:2048
	v_mul_f32_e32 v4, v48, v10
	s_mov_b32 s0, 0x14000
	v_mul_f32_e32 v5, v49, v11
	v_cvt_pk_bf16_f32 v48, v4, v5
	v_add_co_u32_e32 v4, vcc, s0, v2
	v_mul_f32_e32 v49, v51, v13
	s_nop 0
	v_addc_co_u32_e32 v5, vcc, 0, v3, vcc
	flat_store_dword v[4:5], v48
	v_mul_f32_e32 v48, v50, v12
	v_cvt_pk_bf16_f32 v48, v48, v49
	flat_store_dword v[4:5], v48 offset:2048
	v_mul_f32_e32 v4, v52, v14
	s_mov_b32 s0, 0x15000
	v_mul_f32_e32 v5, v53, v15
	v_cvt_pk_bf16_f32 v48, v4, v5
	v_add_co_u32_e32 v4, vcc, s0, v2
	v_mul_f32_e32 v49, v55, v145
	s_nop 0
	v_addc_co_u32_e32 v5, vcc, 0, v3, vcc
	flat_store_dword v[4:5], v48
	v_mul_f32_e32 v48, v54, v144
	v_cvt_pk_bf16_f32 v48, v48, v49
	flat_store_dword v[4:5], v48 offset:2048
	v_mul_f32_e32 v4, v56, v0
	s_mov_b32 s0, 0x16000
	v_mul_f32_e32 v5, v57, v146
	v_cvt_pk_bf16_f32 v48, v4, v5
	v_add_co_u32_e32 v4, vcc, s0, v2
	v_mul_f32_e32 v49, v59, v148
	s_nop 0
	v_addc_co_u32_e32 v5, vcc, 0, v3, vcc
	flat_store_dword v[4:5], v48
	v_mul_f32_e32 v48, v58, v147
	v_cvt_pk_bf16_f32 v48, v48, v49
	flat_store_dword v[4:5], v48 offset:2048
	v_mul_f32_e32 v4, v60, v6
	s_mov_b32 s0, 0x17000
	v_mul_f32_e32 v5, v61, v7
	v_cvt_pk_bf16_f32 v48, v4, v5
	v_add_co_u32_e32 v4, vcc, s0, v2
	v_mul_f32_e32 v49, v63, v9
	s_nop 0
	v_addc_co_u32_e32 v5, vcc, 0, v3, vcc
	flat_store_dword v[4:5], v48
	v_mul_f32_e32 v48, v62, v8
	v_cvt_pk_bf16_f32 v48, v48, v49
	flat_store_dword v[4:5], v48 offset:2048
	v_mul_f32_e32 v4, v32, v10
	v_mul_f32_e32 v5, v33, v11
	v_cvt_pk_bf16_f32 v32, v4, v5
	v_add_co_u32_e32 v4, vcc, s20, v2
	v_mul_f32_e32 v33, v35, v13
	s_nop 0
	v_addc_co_u32_e32 v5, vcc, 0, v3, vcc
	flat_store_dword v[4:5], v32
	v_mul_f32_e32 v32, v34, v12
	v_cvt_pk_bf16_f32 v32, v32, v33
	flat_store_dword v[4:5], v32 offset:2048
	v_mul_f32_e32 v4, v36, v14
	s_mov_b32 s0, 0x19000
	v_mul_f32_e32 v5, v37, v15
	v_cvt_pk_bf16_f32 v32, v4, v5
	v_add_co_u32_e32 v4, vcc, s0, v2
	v_mul_f32_e32 v33, v39, v145
	s_nop 0
	v_addc_co_u32_e32 v5, vcc, 0, v3, vcc
	flat_store_dword v[4:5], v32
	v_mul_f32_e32 v32, v38, v144
	v_cvt_pk_bf16_f32 v32, v32, v33
	flat_store_dword v[4:5], v32 offset:2048
	v_mul_f32_e32 v4, v40, v0
	s_mov_b32 s0, 0x1a000
	v_mul_f32_e32 v5, v41, v146
	v_cvt_pk_bf16_f32 v32, v4, v5
	v_add_co_u32_e32 v4, vcc, s0, v2
	v_mul_f32_e32 v33, v43, v148
	s_nop 0
	v_addc_co_u32_e32 v5, vcc, 0, v3, vcc
	flat_store_dword v[4:5], v32
	v_mul_f32_e32 v32, v42, v147
	v_cvt_pk_bf16_f32 v32, v32, v33
	flat_store_dword v[4:5], v32 offset:2048
	v_mul_f32_e32 v4, v44, v6
	s_mov_b32 s0, 0x1b000
	v_mul_f32_e32 v5, v45, v7
	v_cvt_pk_bf16_f32 v32, v4, v5
	v_add_co_u32_e32 v4, vcc, s0, v2
	v_mul_f32_e32 v33, v47, v9
	s_nop 0
	v_addc_co_u32_e32 v5, vcc, 0, v3, vcc
	flat_store_dword v[4:5], v32
	v_mul_f32_e32 v32, v46, v8
	v_cvt_pk_bf16_f32 v32, v32, v33
	flat_store_dword v[4:5], v32 offset:2048
	v_mul_f32_e32 v4, v16, v10
	s_mov_b32 s0, 0x1c000
	v_mul_f32_e32 v5, v17, v11
	v_cvt_pk_bf16_f32 v10, v4, v5
	v_add_co_u32_e32 v4, vcc, s0, v2
	v_mul_f32_e32 v11, v19, v13
	s_nop 0
	v_addc_co_u32_e32 v5, vcc, 0, v3, vcc
	flat_store_dword v[4:5], v10
	v_mul_f32_e32 v10, v18, v12
	v_cvt_pk_bf16_f32 v10, v10, v11
	flat_store_dword v[4:5], v10 offset:2048
	v_mul_f32_e32 v4, v20, v14
	s_mov_b32 s0, 0x1d000
	v_mul_f32_e32 v5, v21, v15
	v_cvt_pk_bf16_f32 v10, v4, v5
	v_add_co_u32_e32 v4, vcc, s0, v2
	v_mul_f32_e32 v11, v23, v145
	s_nop 0
	v_addc_co_u32_e32 v5, vcc, 0, v3, vcc
	flat_store_dword v[4:5], v10
	v_mul_f32_e32 v10, v22, v144
	v_cvt_pk_bf16_f32 v10, v10, v11
	flat_store_dword v[4:5], v10 offset:2048
	v_mul_f32_e32 v0, v24, v0
	v_mul_f32_e32 v4, v25, v146
	s_mov_b32 s0, 0x1e000
	v_cvt_pk_bf16_f32 v0, v0, v4
	v_add_co_u32_e32 v4, vcc, s0, v2
	v_mul_f32_e32 v10, v27, v148
	s_nop 0
	v_addc_co_u32_e32 v5, vcc, 0, v3, vcc
	flat_store_dword v[4:5], v0
	v_mul_f32_e32 v0, v26, v147
	v_cvt_pk_bf16_f32 v0, v0, v10
	s_mov_b32 s0, 0x1f000
	flat_store_dword v[4:5], v0 offset:2048
	v_mul_f32_e32 v0, v28, v6
	v_add_co_u32_e32 v2, vcc, s0, v2
	v_mul_f32_e32 v4, v29, v7
	v_cvt_pk_bf16_f32 v0, v0, v4
	s_nop 0
	v_addc_co_u32_e32 v3, vcc, 0, v3, vcc
	flat_store_dword v[2:3], v0
	v_mul_f32_e32 v0, v30, v8
	v_mul_f32_e32 v4, v31, v9
	v_cvt_pk_bf16_f32 v0, v0, v4
	flat_store_dword v[2:3], v0 offset:2048
	s_getreg_b32 s0, hwreg(HW_REG_HW_ID, 0, 6)
	s_lshl_b32 s0, s0, 2
	s_and_b32 s0, s0, 0xfc
	s_add_i32 s0, s0, 0x24c40
	v_mov_b32_e32 v0, s0
	ds_read_b32 v0, v0
	v_mbcnt_lo_u32_b32 v2, -1, 0
	v_mbcnt_hi_u32_b32 v2, -1, v2
	v_mov_b32_e32 v221, v1
	s_mov_b64 s[6:7], 0x4000
	v_readlane_b32 s62, v255, 18
	s_waitcnt lgkmcnt(0)
; __device__ __forceinline__ int v_rd_base(int lane) { return ((lane & 3) << 3) | (((lane >> 2) & 3) << 6) | (((lane >> 4) & 1) << 5) | (((lane >> 5) & 1) << 8); }
; template <int LD>
; __device__ __forceinline__ void attn256_body(const bf16_t* __restrict__ Qb, const bf16_t* __restrict__ Kh, const unsigned char* __restrict__ Vimg, int seq, char* lds, LAS unsigned char* ldsl,
;                                              f32x16 (&o)[8], float (&rli)[16]) {
;   int tid = TIDX(); asm volatile("" : "+v"(tid));
;   const int wid = __builtin_amdgcn_readfirstlane(tid >> 6), lane = tid & 63, r32 = lane & 31, hi = lane >> 5;
;   float* wsf = (float*)(lds + LDS_XCH) + wid * 64; float* li_l = wsf; float* al_l = wsf + 32;
;   float m_reg = -1e30f, l_reg = 0.f; bf16x8 qr[8];
; #pragma unroll
;   for (int d = 0; d < 8; ++d) o[d] = f32x16{};
;   const bf16_t* Qw = Qb + (size_t)(wid * 32 + r32) * LD + hi * 8;
; #pragma unroll
;   for (int d0 = 0; d0 < 8; ++d0) qr[d0] = *(const bf16x8*)(Qw + d0 * 16);
;   unsigned voffK[2], voffV[2];
; #pragma unroll
;   for (int i = 0; i < 2; ++i) { const int b = (i * 512 + tid) * 16;
;     { const int row = b >> 8, cB = (b & 255) ^ ((row & 7) << 4); voffK[i] = (unsigned)(row * LD) * 2u + (unsigned)cB; }
;     { const int st = b >> 9, w = b & 511, kk = (st >> 2) * 8 + (w >> 6), c = (st & 3) * 32 + ((w & 63) >> 1);
;       (void)kk; (void)c; voffV[i] = (unsigned)tid * 16u; } }
;   const unsigned ldsw = (unsigned)wid * 1024u;
;     ...
;   const int NT = seq / 64;
;   const int vb0 = (int)(uintptr_t)lds + 16384 + v_rd_base(lane);
;   const int kbase = (int)(uintptr_t)lds + r32 * 256;
;   constexpr float C = ATT_SCALE * LOG2E;
;   __syncthreads();
;   A2_DMA(0, 0);
;   asm volatile("s_waitcnt vmcnt(0)" ::: "memory"); __syncthreads();
;   if (wid >= 4) __builtin_amdgcn_s_setprio(1);
;   for (int j = 0; j < NT; ++j) {
;     const int cur = j & 1;
;     if (j + 1 < NT) { if (cur) A2_DMA(0, (j + 1) * 64); else A2_DMA(1, (j + 1) * 64); }
;     f32x16 p0 = f32x16{}, p1 = f32x16{}; float pmax;
;     { int ka[4];
; #pragma unroll
;       for (int q = 0; q < 4; ++q) ka[q] = kbase + cur * A2_STAGE + (((2 * q + hi) ^ (r32 & 7)) << 4);
	v_readfirstlane_b32 s0, v0
	v_readlane_b32 s63, v255, 19
	s_nop 0
	v_lshl_add_u32 v3, s0, 6, v2
	s_nop 0
	v_readfirstlane_b32 s4, v3
	v_and_b32_e32 v4, 31, v3
	s_ashr_i32 s5, s4, 6
	v_lshl_or_b32 v6, s5, 5, v4
	v_ashrrev_i32_e32 v7, 31, v6
	v_bfe_u32 v2, v3, 5, 1
	v_lshlrev_b64 v[6:7], 14, v[6:7]
	v_lshlrev_b32_e32 v220, 4, v2
	v_lshl_add_u64 v[6:7], s[34:35], 0, v[6:7]
	v_bfe_i32 v5, v3, 4, 24
	v_lshl_add_u64 v[6:7], v[6:7], 0, v[220:221]
	v_lshlrev_b32_e32 v0, 4, v3
	v_lshlrev_b32_e32 v8, 4, v5
	global_load_dwordx4 v[162:165], v[6:7], off
	global_load_dwordx4 v[166:169], v[6:7], off offset:32
	global_load_dwordx4 v[170:173], v[6:7], off offset:64
	global_load_dwordx4 v[174:177], v[6:7], off offset:96
	global_load_dwordx4 v[178:181], v[6:7], off offset:128
	global_load_dwordx4 v[182:185], v[6:7], off offset:160
	global_load_dwordx4 v[186:189], v[6:7], off offset:192
	global_load_dwordx4 v[190:193], v[6:7], off offset:224
	v_and_b32_e32 v7, 0xf0, v0
	v_and_b32_e32 v6, 0x70, v8
	v_lshlrev_b32_e32 v5, 14, v5
	v_bitop3_b32 v10, v6, v5, v7 bitop3:0xde
	v_add_u32_e32 v6, 0x2000, v0
	v_ashrrev_i32_e32 v6, 8, v6
	s_lshl_b32 s0, s5, 10
	v_lshlrev_b32_e32 v9, 4, v6
	s_add_i32 s0, s0, 0
	v_and_b32_e32 v11, 0x70, v9
	v_lshlrev_b32_e32 v6, 14, v6
	s_mov_b32 m0, s0
	v_bitop3_b32 v11, v11, v6, v7 bitop3:0xde
	s_waitcnt vmcnt(63) expcnt(7) lgkmcnt(15)
	s_barrier
	global_load_lds_dwordx4 v10, s[24:25]
	s_add_i32 m0, s0, 0x2000
	s_add_i32 s1, s0, 0x4000
	global_load_lds_dwordx4 v11, s[24:25]
	v_lshl_add_u64 v[10:11], s[12:13], 0, v[0:1]
	s_mov_b32 m0, s1
	s_add_i32 s24, s0, 0x6000
	global_load_lds_dwordx4 v0, s[12:13]
	v_lshl_add_u64 v[12:13], v[10:11], 0, s[54:55]
	s_mov_b32 m0, s24
	s_add_i32 s25, s0, 0x8000
	global_load_lds_dwordx4 v[12:13], off
	v_lshl_add_u64 v[12:13], v[10:11], 0, s[6:7]
	s_mov_b32 m0, s25
	s_mov_b64 s[6:7], 0x6000
	s_add_i32 s28, s0, 0xa000
	global_load_lds_dwordx4 v[12:13], off
	v_lshl_add_u64 v[10:11], v[10:11], 0, s[6:7]
	s_mov_b32 m0, s28
	s_cmp_lt_i32 s5, 4
	global_load_lds_dwordx4 v[10:11], off
	s_waitcnt vmcnt(0)
	s_waitcnt vmcnt(0) lgkmcnt(0)
	s_barrier
	s_cbranch_scc1 .LBB0_675
.LBB0_675:
	s_and_b32 s4, s4, 0x3fffffc0
	s_lshl_b32 s4, s4, 2
	s_add_i32 s29, s4, 0
	v_and_b32_e32 v10, 63, v3
	s_add_i32 s29, s29, 0x24000
	v_and_b32_e32 v13, 7, v3
	v_bitop3_b32 v3, v2, v3, 7 bitop3:0x78
	v_bitop3_b32 v8, v8, v7, s91 bitop3:0x6c
	v_lshlrev_b32_e32 v11, 1, v10
	s_cmp_lg_u32 0, -1
	v_lshlrev_b32_e32 v233, 4, v3
	v_bitop3_b32 v3, v2, v13, 2 bitop3:0x36
	v_bitop3_b32 v7, v9, v7, s91 bitop3:0x6c
	v_lshlrev_b32_e32 v9, 4, v10
	v_lshlrev_b32_e32 v12, 3, v10
	v_and_b32_e32 v11, 32, v11
	s_cselect_b32 s4, 0, 0
	v_lshlrev_b32_e32 v234, 4, v3
	v_bitop3_b32 v3, v2, v13, 4 bitop3:0x36
	v_bitop3_b32 v2, v2, v13, 6 bitop3:0x36
	s_movk_i32 s5, 0x118
	v_lshl_add_u64 v[222:223], s[10:11], 0, v[0:1]
	s_or_b32 s36, s36, 0xa901000
	v_add_u32_e32 v0, v8, v5
	v_and_b32_e32 v9, 0xc0, v9
	v_lshl_add_u32 v221, v4, 8, s4
	v_lshlrev_b32_e32 v236, 4, v2
	v_and_or_b32 v2, v12, s5, v11
	s_addk_i32 s4, 0x4000
	v_lshl_add_u64 v[224:225], s[36:37], 0, v[0:1]
	v_add_u32_e32 v0, v7, v6
	v_mov_b32_e32 v14, v1
	v_mov_b32_e32 v15, v1
	v_cmp_gt_u32_e64 s[38:39], 32, v10
	v_lshl_add_u32 v219, v4, 2, s29
	v_lshlrev_b32_e32 v235, 4, v3
	v_add3_u32 v237, v9, s4, v2
	v_lshl_add_u64 v[226:227], s[36:37], 0, v[0:1]
	v_mov_b32_e32 v0, v1
	v_mov_b32_e32 v2, v1
	v_mov_b32_e32 v3, v1
	v_mov_b32_e32 v4, v1
	v_mov_b32_e32 v5, v1
	v_mov_b32_e32 v6, v1
	v_mov_b32_e32 v7, v1
	v_mov_b32_e32 v8, v1
	v_mov_b32_e32 v9, v1
	v_mov_b32_e32 v10, v1
	v_mov_b32_e32 v11, v1
	v_mov_b32_e32 v12, v1
	v_mov_b32_e32 v13, v1
	v_mov_b64_e32 v[128:129], v[14:15]
	v_mov_b64_e32 v[112:113], v[14:15]
	v_mov_b64_e32 v[96:97], v[14:15]
	v_mov_b64_e32 v[80:81], v[14:15]
	v_mov_b64_e32 v[64:65], v[14:15]
	v_mov_b64_e32 v[48:49], v[14:15]
	v_mov_b64_e32 v[32:33], v[14:15]
	v_mov_b64_e32 v[126:127], v[12:13]
	v_mov_b64_e32 v[124:125], v[10:11]
	v_mov_b64_e32 v[122:123], v[8:9]
	v_mov_b64_e32 v[120:121], v[6:7]
	v_mov_b64_e32 v[118:119], v[4:5]
	v_mov_b64_e32 v[116:117], v[2:3]
	v_mov_b64_e32 v[114:115], v[0:1]
	v_mov_b64_e32 v[110:111], v[12:13]
	v_mov_b64_e32 v[108:109], v[10:11]
	v_mov_b64_e32 v[106:107], v[8:9]
	v_mov_b64_e32 v[104:105], v[6:7]
	v_mov_b64_e32 v[102:103], v[4:5]
	v_mov_b64_e32 v[100:101], v[2:3]
	v_mov_b64_e32 v[98:99], v[0:1]
	v_mov_b64_e32 v[94:95], v[12:13]
	v_mov_b64_e32 v[92:93], v[10:11]
	v_mov_b64_e32 v[90:91], v[8:9]
	v_mov_b64_e32 v[88:89], v[6:7]
	v_mov_b64_e32 v[86:87], v[4:5]
	v_mov_b64_e32 v[84:85], v[2:3]
	v_mov_b64_e32 v[82:83], v[0:1]
	v_mov_b64_e32 v[78:79], v[12:13]
	v_mov_b64_e32 v[76:77], v[10:11]
	v_mov_b64_e32 v[74:75], v[8:9]
	v_mov_b64_e32 v[72:73], v[6:7]
	v_mov_b64_e32 v[70:71], v[4:5]
	v_mov_b64_e32 v[68:69], v[2:3]
	v_mov_b64_e32 v[66:67], v[0:1]
	v_mov_b64_e32 v[62:63], v[12:13]
	v_mov_b64_e32 v[60:61], v[10:11]
	v_mov_b64_e32 v[58:59], v[8:9]
	v_mov_b64_e32 v[56:57], v[6:7]
	v_mov_b64_e32 v[54:55], v[4:5]
	v_mov_b64_e32 v[52:53], v[2:3]
	v_mov_b64_e32 v[50:51], v[0:1]
	v_mov_b64_e32 v[46:47], v[12:13]
	v_mov_b64_e32 v[44:45], v[10:11]
	v_mov_b64_e32 v[42:43], v[8:9]
	v_mov_b64_e32 v[40:41], v[6:7]
	v_mov_b64_e32 v[38:39], v[4:5]
	v_mov_b64_e32 v[36:37], v[2:3]
	v_mov_b64_e32 v[34:35], v[0:1]
	v_mov_b64_e32 v[30:31], v[12:13]
	v_mov_b64_e32 v[28:29], v[10:11]
	v_mov_b64_e32 v[26:27], v[8:9]
	v_mov_b64_e32 v[24:25], v[6:7]
	v_mov_b64_e32 v[22:23], v[4:5]
	v_mov_b64_e32 v[20:21], v[2:3]
	v_mov_b64_e32 v[18:19], v[0:1]
	v_mov_b64_e32 v[16:17], v[14:15]
	s_mov_b32 s34, 0
	s_add_i32 s35, s0, 0xc000
	s_add_i32 s44, s0, 0x10000
	s_add_i32 s45, s0, 0x12000
	s_add_i32 s48, s0, 0x14000
	s_add_i32 s49, s0, 0x16000
	v_mov_b32_e32 v239, 0
	v_mov_b32_e32 v238, 0xf149f2ca
	v_mov_b64_e32 v[14:15], v[12:13]
	v_mov_b64_e32 v[12:13], v[10:11]
	v_mov_b64_e32 v[10:11], v[8:9]
	v_mov_b64_e32 v[8:9], v[6:7]
	v_mov_b64_e32 v[6:7], v[4:5]
	v_mov_b64_e32 v[4:5], v[2:3]
	v_mov_b64_e32 v[2:3], v[0:1]
	s_and_b32 s4, s34, 1
	s_cmpk_eq_i32 s34, 0xff
	s_cbranch_scc1 .LBB0_677
